# gate epilogue: hipcc correctly-rounded sqrt expansion (17 instr) replaced by single v_sqrt_f32 (f32, 1ulp, same class as baseline's rcp/exp2)
# speedup vs baseline: 1.0026x; 1.0026x over previous
.LBB0_466:
	s_add_u32 s57, s44, s56
	s_addc_u32 s67, s45, 0
	s_add_u32 s60, s57, 0x100
	s_addc_u32 s61, s67, 0
	s_and_b64 s[58:59], s[54:55], exec
	s_cselect_b32 s61, s31, s61
	s_cselect_b32 s60, s88, s60
	s_add_u32 s56, s8, s56
	s_addc_u32 s58, s9, 0
	s_add_u32 s56, s56, 0x100
	s_addc_u32 s58, s58, 0
	s_and_b64 s[54:55], s[54:55], exec
	s_cselect_b32 s63, s29, s58
	s_cselect_b32 s62, s89, s56
	s_add_u32 s66, s57, 0x100080
	s_addc_u32 s67, s67, 0
	s_add_i32 vcc_hi, s85, s73
	s_add_i32 m0, s4, 0xc000
	s_add_i32 s75, s4, 0xe000
	s_add_i32 vcc_lo, vcc_hi, 0x2000
	s_add_u32 s58, s62, 0x10000
	s_addc_u32 s59, s63, 0
	s_add_i32 s97, s86, s73
	ds_read_b128 v[40:43], v189
	ds_read_b128 v[44:47], v189 offset:1024
	ds_read_b128 v[48:51], v189 offset:2048
	ds_read_b128 v[60:63], v189 offset:3072
	s_add_i32 s96, s97, 0x2000
	s_add_i32 s95, 0, 0x18000
	s_add_u32 s56, s60, 0x100000
	s_addc_u32 s57, s61, 0
	s_add_i32 s94, s95, s73
	s_add_i32 s93, 0, 0x1c000
	s_add_i32 s92, s94, 0x2000
	s_add_u32 s54, s62, 0x10080
	s_addc_u32 s55, s63, 0
	s_add_i32 s91, s93, s73
	s_add_i32 s90, s91, 0x2000
	v_lshl_add_u64 v[176:177], s[66:67], 0, v[180:181]
	ds_read_b128 v[64:67], v212
	ds_read_b128 v[68:71], v212 offset:1024
	ds_read_b128 v[72:75], v212 offset:2048
	ds_read_b128 v[92:95], v212 offset:3072
	ds_read_b128 v[112:115], v212 offset:4096
	ds_read_b128 v[132:135], v212 offset:5120
	ds_read_b128 v[152:155], v212 offset:6144
	ds_read_b128 v[172:175], v212 offset:7168
	global_load_lds_dwordx4 v[176:177], off
	v_lshl_add_u64 v[176:177], s[66:67], 0, v[184:185]
	s_mov_b32 m0, s75
	s_nop 0
	global_load_lds_dwordx4 v[176:177], off
	s_waitcnt lgkmcnt(8)
	s_barrier
	s_waitcnt lgkmcnt(0)
	s_setprio 1
	s_waitcnt lgkmcnt(0)
	v_mfma_f32_16x16x32_bf16 v[168:171], v[40:43], v[64:67], v[168:171]
	v_mfma_f32_16x16x32_bf16 v[160:163], v[48:51], v[64:67], v[160:163]
	v_mfma_f32_16x16x32_bf16 v[148:151], v[40:43], v[72:75], v[148:151]
	v_mfma_f32_16x16x32_bf16 v[140:143], v[48:51], v[72:75], v[140:143]
	v_mfma_f32_16x16x32_bf16 v[128:131], v[40:43], v[112:115], v[128:131]
	v_mfma_f32_16x16x32_bf16 v[120:123], v[48:51], v[112:115], v[120:123]
	v_mfma_f32_16x16x32_bf16 v[108:111], v[40:43], v[152:155], v[108:111]
	v_mfma_f32_16x16x32_bf16 v[100:103], v[48:51], v[152:155], v[100:103]
	v_mfma_f32_16x16x32_bf16 v[168:171], v[44:47], v[68:71], v[168:171]
	v_mfma_f32_16x16x32_bf16 v[160:163], v[60:63], v[68:71], v[160:163]
	v_mfma_f32_16x16x32_bf16 v[148:151], v[44:47], v[92:95], v[148:151]
	v_mfma_f32_16x16x32_bf16 v[140:143], v[60:63], v[92:95], v[140:143]
	v_mfma_f32_16x16x32_bf16 v[128:131], v[44:47], v[132:135], v[128:131]
	v_mfma_f32_16x16x32_bf16 v[120:123], v[60:63], v[132:135], v[120:123]
	v_mfma_f32_16x16x32_bf16 v[108:111], v[44:47], v[172:175], v[108:111]
	v_mfma_f32_16x16x32_bf16 v[100:103], v[60:63], v[172:175], v[100:103]
	s_setprio 0
	s_barrier
	s_mov_b32 m0, vcc_hi
	v_lshl_add_u64 v[208:209], s[62:63], 0, v[182:183]
	ds_read_b128 v[176:179], v213
	ds_read_b128 v[204:207], v213 offset:1024
	ds_read_b128 v[216:219], v213 offset:2048
	ds_read_b128 v[220:223], v213 offset:3072
	global_load_lds_dwordx4 v[208:209], off
	v_lshl_add_u64 v[232:233], s[62:63], 0, v[186:187]
	s_mov_b32 m0, vcc_lo
	s_nop 0
	global_load_lds_dwordx4 v[232:233], off
	s_barrier
	s_waitcnt lgkmcnt(0)
	s_setprio 1
	s_waitcnt lgkmcnt(0)
	v_mfma_f32_16x16x32_bf16 v[164:167], v[176:179], v[64:67], v[164:167]
	v_mfma_f32_16x16x32_bf16 v[64:67], v[216:219], v[64:67], v[156:159]
	v_mfma_f32_16x16x32_bf16 v[164:167], v[204:207], v[68:71], v[164:167]
	v_mfma_f32_16x16x32_bf16 v[64:67], v[220:223], v[68:71], v[64:67]
	v_mfma_f32_16x16x32_bf16 v[68:71], v[176:179], v[72:75], v[144:147]
	v_mfma_f32_16x16x32_bf16 v[72:75], v[216:219], v[72:75], v[136:139]
	v_mfma_f32_16x16x32_bf16 v[104:107], v[176:179], v[152:155], v[104:107]
	v_mfma_f32_16x16x32_bf16 v[96:99], v[216:219], v[152:155], v[96:99]
	v_mfma_f32_16x16x32_bf16 v[68:71], v[204:207], v[92:95], v[68:71]
	v_mfma_f32_16x16x32_bf16 v[72:75], v[220:223], v[92:95], v[72:75]
	v_mfma_f32_16x16x32_bf16 v[92:95], v[176:179], v[112:115], v[124:127]
	v_mfma_f32_16x16x32_bf16 v[112:115], v[216:219], v[112:115], v[116:119]
	v_mfma_f32_16x16x32_bf16 v[104:107], v[204:207], v[172:175], v[104:107]
	v_mfma_f32_16x16x32_bf16 v[96:99], v[220:223], v[172:175], v[96:99]
	v_mfma_f32_16x16x32_bf16 v[92:95], v[204:207], v[132:135], v[92:95]
	v_mfma_f32_16x16x32_bf16 v[112:115], v[220:223], v[132:135], v[112:115]
	s_setprio 0
	s_mov_b32 m0, s4
	v_lshl_add_u64 v[234:235], s[60:61], 0, v[180:181]
	s_barrier
	ds_read_b128 v[116:119], v212 offset:16384
	ds_read_b128 v[124:127], v212 offset:17408
	ds_read_b128 v[132:135], v212 offset:18432
	ds_read_b128 v[136:139], v212 offset:19456
	ds_read_b128 v[144:147], v212 offset:20480
	ds_read_b128 v[152:155], v212 offset:21504
	ds_read_b128 v[156:159], v212 offset:22528
	ds_read_b128 v[172:175], v212 offset:23552
	global_load_lds_dwordx4 v[234:235], off
	v_lshl_add_u64 v[236:237], s[60:61], 0, v[184:185]
	s_mov_b32 m0, s78
	s_nop 0
	global_load_lds_dwordx4 v[236:237], off
	s_barrier
	s_waitcnt lgkmcnt(0)
	s_setprio 1
	s_waitcnt lgkmcnt(0)
	v_mfma_f32_16x16x32_bf16 v[88:91], v[40:43], v[116:119], v[88:91]
	v_mfma_f32_16x16x32_bf16 v[80:83], v[48:51], v[116:119], v[80:83]
	v_mfma_f32_16x16x32_bf16 v[56:59], v[40:43], v[132:135], v[56:59]
	v_mfma_f32_16x16x32_bf16 v[36:39], v[48:51], v[132:135], v[36:39]
	v_mfma_f32_16x16x32_bf16 v[28:31], v[40:43], v[144:147], v[28:31]
	v_mfma_f32_16x16x32_bf16 v[20:23], v[48:51], v[144:147], v[20:23]
	v_mfma_f32_16x16x32_bf16 v[12:15], v[40:43], v[156:159], v[12:15]
	v_mfma_f32_16x16x32_bf16 v[4:7], v[48:51], v[156:159], v[4:7]
	v_mfma_f32_16x16x32_bf16 v[88:91], v[44:47], v[124:127], v[88:91]
	v_mfma_f32_16x16x32_bf16 v[80:83], v[60:63], v[124:127], v[80:83]
	v_mfma_f32_16x16x32_bf16 v[56:59], v[44:47], v[136:139], v[56:59]
	v_mfma_f32_16x16x32_bf16 v[36:39], v[60:63], v[136:139], v[36:39]
	v_mfma_f32_16x16x32_bf16 v[28:31], v[44:47], v[152:155], v[28:31]
	v_mfma_f32_16x16x32_bf16 v[20:23], v[60:63], v[152:155], v[20:23]
	v_mfma_f32_16x16x32_bf16 v[12:15], v[44:47], v[172:175], v[12:15]
	v_mfma_f32_16x16x32_bf16 v[4:7], v[60:63], v[172:175], v[4:7]
	s_setprio 0
	s_barrier
	s_mov_b32 m0, s97
	v_lshl_add_u64 v[40:41], s[58:59], 0, v[182:183]
	global_load_lds_dwordx4 v[40:41], off
	v_lshl_add_u64 v[40:41], s[58:59], 0, v[186:187]
	s_mov_b32 m0, s96
	s_nop 0
	global_load_lds_dwordx4 v[40:41], off
	s_waitcnt vmcnt(6)
	s_barrier
	s_setprio 1
	v_mfma_f32_16x16x32_bf16 v[32:35], v[216:219], v[132:135], v[32:35]
	v_mfma_f32_16x16x32_bf16 v[24:27], v[176:179], v[144:147], v[24:27]
	v_mfma_f32_16x16x32_bf16 v[16:19], v[216:219], v[144:147], v[16:19]
	v_mfma_f32_16x16x32_bf16 v[8:11], v[176:179], v[156:159], v[8:11]
	v_mfma_f32_16x16x32_bf16 v[0:3], v[216:219], v[156:159], v[0:3]
	v_mfma_f32_16x16x32_bf16 v[40:43], v[176:179], v[116:119], v[84:87]
	v_mfma_f32_16x16x32_bf16 v[44:47], v[216:219], v[116:119], v[76:79]
	v_mfma_f32_16x16x32_bf16 v[48:51], v[176:179], v[132:135], v[52:55]
	v_mfma_f32_16x16x32_bf16 v[32:35], v[220:223], v[136:139], v[32:35]
	v_mfma_f32_16x16x32_bf16 v[24:27], v[204:207], v[152:155], v[24:27]
	v_mfma_f32_16x16x32_bf16 v[16:19], v[220:223], v[152:155], v[16:19]
	v_mfma_f32_16x16x32_bf16 v[8:11], v[204:207], v[172:175], v[8:11]
	v_mfma_f32_16x16x32_bf16 v[0:3], v[220:223], v[172:175], v[0:3]
	v_mfma_f32_16x16x32_bf16 v[40:43], v[204:207], v[124:127], v[40:43]
	v_mfma_f32_16x16x32_bf16 v[44:47], v[220:223], v[124:127], v[44:47]
	v_mfma_f32_16x16x32_bf16 v[48:51], v[204:207], v[136:139], v[48:51]
	s_setprio 0
	v_add_u32_e32 v84, s95, v211
	s_barrier
	ds_read_b128 v[52:55], v84
	ds_read_b128 v[60:63], v84 offset:1024
	ds_read_b128 v[76:79], v84 offset:2048
	ds_read_b128 v[84:87], v84 offset:3072
	s_mov_b32 m0, s79
	v_lshl_add_u64 v[144:145], s[56:57], 0, v[180:181]
	ds_read_b128 v[116:119], v212 offset:32768
	ds_read_b128 v[124:127], v212 offset:33792
	ds_read_b128 v[132:135], v212 offset:34816
	ds_read_b128 v[136:139], v212 offset:35840
	ds_read_b128 v[152:155], v212 offset:36864
	ds_read_b128 v[172:175], v212 offset:37888
	ds_read_b128 v[176:179], v212 offset:38912
	ds_read_b128 v[204:207], v212 offset:39936
	global_load_lds_dwordx4 v[144:145], off
	v_lshl_add_u64 v[144:145], s[56:57], 0, v[184:185]
	s_mov_b32 m0, s81
	s_nop 0
	global_load_lds_dwordx4 v[144:145], off
	s_waitcnt lgkmcnt(8)
	s_barrier
	s_waitcnt lgkmcnt(0)
	s_setprio 1
	s_waitcnt lgkmcnt(0)
	v_mfma_f32_16x16x32_bf16 v[144:147], v[52:55], v[116:119], v[168:171]
	v_mfma_f32_16x16x32_bf16 v[168:171], v[60:63], v[124:127], v[144:147]
	v_mfma_f32_16x16x32_bf16 v[144:147], v[76:79], v[116:119], v[160:163]
	v_mfma_f32_16x16x32_bf16 v[160:163], v[84:87], v[124:127], v[144:147]
	v_mfma_f32_16x16x32_bf16 v[144:147], v[52:55], v[132:135], v[148:151]
	v_mfma_f32_16x16x32_bf16 v[140:143], v[76:79], v[132:135], v[140:143]
	v_mfma_f32_16x16x32_bf16 v[128:131], v[52:55], v[152:155], v[128:131]
	v_mfma_f32_16x16x32_bf16 v[120:123], v[76:79], v[152:155], v[120:123]
	v_mfma_f32_16x16x32_bf16 v[108:111], v[52:55], v[176:179], v[108:111]
	v_mfma_f32_16x16x32_bf16 v[100:103], v[76:79], v[176:179], v[100:103]
	v_mfma_f32_16x16x32_bf16 v[148:151], v[60:63], v[136:139], v[144:147]
	v_mfma_f32_16x16x32_bf16 v[140:143], v[84:87], v[136:139], v[140:143]
	v_mfma_f32_16x16x32_bf16 v[128:131], v[60:63], v[172:175], v[128:131]
	v_mfma_f32_16x16x32_bf16 v[120:123], v[84:87], v[172:175], v[120:123]
	v_mfma_f32_16x16x32_bf16 v[108:111], v[60:63], v[204:207], v[108:111]
	v_mfma_f32_16x16x32_bf16 v[100:103], v[84:87], v[204:207], v[100:103]
	s_setprio 0
	s_barrier
	v_add_u32_e32 v144, s93, v211
	s_mov_b32 m0, s94
	ds_read_b128 v[216:219], v144
	ds_read_b128 v[220:223], v144 offset:1024
	ds_read_b128 v[224:227], v144 offset:2048
	ds_read_b128 v[228:231], v144 offset:3072
	v_lshl_add_u64 v[144:145], v[208:209], 0, s[22:23]
	global_load_lds_dwordx4 v[144:145], off
	v_lshl_add_u64 v[144:145], v[232:233], 0, s[22:23]
	s_mov_b32 m0, s92
	s_nop 0
	global_load_lds_dwordx4 v[144:145], off
	s_barrier
	s_waitcnt lgkmcnt(0)
	s_setprio 1
	s_waitcnt lgkmcnt(0)
	v_mfma_f32_16x16x32_bf16 v[64:67], v[224:227], v[116:119], v[64:67]
	v_mfma_f32_16x16x32_bf16 v[144:147], v[216:219], v[116:119], v[164:167]
	v_mfma_f32_16x16x32_bf16 v[156:159], v[228:231], v[124:127], v[64:67]
	v_mfma_f32_16x16x32_bf16 v[64:67], v[216:219], v[132:135], v[68:71]
	v_mfma_f32_16x16x32_bf16 v[164:167], v[220:223], v[124:127], v[144:147]
	v_mfma_f32_16x16x32_bf16 v[144:147], v[220:223], v[136:139], v[64:67]
	v_mfma_f32_16x16x32_bf16 v[64:67], v[224:227], v[132:135], v[72:75]
	v_mfma_f32_16x16x32_bf16 v[136:139], v[228:231], v[136:139], v[64:67]
	v_mfma_f32_16x16x32_bf16 v[64:67], v[216:219], v[152:155], v[92:95]
	v_mfma_f32_16x16x32_bf16 v[124:127], v[220:223], v[172:175], v[64:67]
	v_mfma_f32_16x16x32_bf16 v[64:67], v[224:227], v[152:155], v[112:115]
	v_mfma_f32_16x16x32_bf16 v[116:119], v[228:231], v[172:175], v[64:67]
	v_mfma_f32_16x16x32_bf16 v[64:67], v[216:219], v[176:179], v[104:107]
	v_mfma_f32_16x16x32_bf16 v[104:107], v[220:223], v[204:207], v[64:67]
	v_mfma_f32_16x16x32_bf16 v[64:67], v[224:227], v[176:179], v[96:99]
	v_mfma_f32_16x16x32_bf16 v[96:99], v[228:231], v[204:207], v[64:67]
	s_setprio 0
	s_mov_b32 m0, s83
	v_lshl_add_u64 v[176:177], v[234:235], 0, s[22:23]
	s_barrier
	s_nop 2
	ds_read_b128 v[64:67], v212 offset:49152
	ds_read_b128 v[68:71], v212 offset:50176
	ds_read_b128 v[72:75], v212 offset:51200
	ds_read_b128 v[92:95], v212 offset:52224
	ds_read_b128 v[112:115], v212 offset:53248
	ds_read_b128 v[132:135], v212 offset:54272
	ds_read_b128 v[152:155], v212 offset:55296
	ds_read_b128 v[172:175], v212 offset:56320
	global_load_lds_dwordx4 v[176:177], off
	v_lshl_add_u64 v[176:177], v[236:237], 0, s[22:23]
	s_mov_b32 m0, s84
	s_nop 0
	global_load_lds_dwordx4 v[176:177], off
	s_barrier
	s_waitcnt lgkmcnt(0)
	s_setprio 1
	s_waitcnt lgkmcnt(0)
	v_mfma_f32_16x16x32_bf16 v[88:91], v[52:55], v[64:67], v[88:91]
	v_mfma_f32_16x16x32_bf16 v[80:83], v[76:79], v[64:67], v[80:83]
	v_mfma_f32_16x16x32_bf16 v[56:59], v[52:55], v[72:75], v[56:59]
	v_mfma_f32_16x16x32_bf16 v[36:39], v[76:79], v[72:75], v[36:39]
	v_mfma_f32_16x16x32_bf16 v[28:31], v[52:55], v[112:115], v[28:31]
	v_mfma_f32_16x16x32_bf16 v[20:23], v[76:79], v[112:115], v[20:23]
	v_mfma_f32_16x16x32_bf16 v[12:15], v[52:55], v[152:155], v[12:15]
	v_mfma_f32_16x16x32_bf16 v[4:7], v[76:79], v[152:155], v[4:7]
	v_mfma_f32_16x16x32_bf16 v[88:91], v[60:63], v[68:71], v[88:91]
	v_mfma_f32_16x16x32_bf16 v[80:83], v[84:87], v[68:71], v[80:83]
	v_mfma_f32_16x16x32_bf16 v[56:59], v[60:63], v[92:95], v[56:59]
	v_mfma_f32_16x16x32_bf16 v[36:39], v[84:87], v[92:95], v[36:39]
	v_mfma_f32_16x16x32_bf16 v[28:31], v[60:63], v[132:135], v[28:31]
	v_mfma_f32_16x16x32_bf16 v[20:23], v[84:87], v[132:135], v[20:23]
	v_mfma_f32_16x16x32_bf16 v[12:15], v[60:63], v[172:175], v[12:15]
	v_mfma_f32_16x16x32_bf16 v[4:7], v[84:87], v[172:175], v[4:7]
	s_setprio 0
	s_barrier
	s_mov_b32 m0, s91
	v_lshl_add_u64 v[52:53], s[54:55], 0, v[182:183]
	global_load_lds_dwordx4 v[52:53], off
	v_lshl_add_u64 v[52:53], s[54:55], 0, v[186:187]
	s_mov_b32 m0, s90
	s_nop 0
	global_load_lds_dwordx4 v[52:53], off
	s_waitcnt vmcnt(6)
	s_barrier
	s_setprio 1
	v_mfma_f32_16x16x32_bf16 v[40:43], v[216:219], v[64:67], v[40:43]
	v_mfma_f32_16x16x32_bf16 v[84:87], v[220:223], v[68:71], v[40:43]
	v_mfma_f32_16x16x32_bf16 v[40:43], v[224:227], v[64:67], v[44:47]
	v_mfma_f32_16x16x32_bf16 v[76:79], v[228:231], v[68:71], v[40:43]
	v_mfma_f32_16x16x32_bf16 v[40:43], v[216:219], v[72:75], v[48:51]
	v_mfma_f32_16x16x32_bf16 v[32:35], v[224:227], v[72:75], v[32:35]
	v_mfma_f32_16x16x32_bf16 v[24:27], v[216:219], v[112:115], v[24:27]
	v_mfma_f32_16x16x32_bf16 v[16:19], v[224:227], v[112:115], v[16:19]
	v_mfma_f32_16x16x32_bf16 v[8:11], v[216:219], v[152:155], v[8:11]
	v_mfma_f32_16x16x32_bf16 v[0:3], v[224:227], v[152:155], v[0:3]
	v_mfma_f32_16x16x32_bf16 v[52:55], v[220:223], v[92:95], v[40:43]
	v_mfma_f32_16x16x32_bf16 v[32:35], v[228:231], v[92:95], v[32:35]
	v_mfma_f32_16x16x32_bf16 v[24:27], v[220:223], v[132:135], v[24:27]
	v_mfma_f32_16x16x32_bf16 v[16:19], v[228:231], v[132:135], v[16:19]
	v_mfma_f32_16x16x32_bf16 v[8:11], v[220:223], v[172:175], v[8:11]
	v_mfma_f32_16x16x32_bf16 v[0:3], v[228:231], v[172:175], v[0:3]
	s_setprio 0
	s_movk_i32 s56, 0x100
	s_andn2_b64 vcc, exec, s[48:49]
	s_mov_b64 s[54:55], -1
	s_mov_b64 s[48:49], 0
	s_barrier
	s_cbranch_vccz .LBB0_466
	v_lshl_or_b32 v40, s1, 7, v190
	v_lshl_add_u32 v72, s0, 8, v188
	v_ashrrev_i32_e32 v41, 31, v40
	v_ashrrev_i32_e32 v73, 31, v72
	v_lshl_add_u64 v[74:75], v[40:41], 1, s[14:15]
	v_lshlrev_b64 v[42:43], 13, v[72:73]
	v_lshl_add_u64 v[42:43], v[74:75], 0, v[42:43]
	v_lshlrev_b64 v[40:41], 2, v[40:41]
	global_load_dwordx4 v[216:219], v[42:43], off nt
	v_lshl_add_u64 v[42:43], s[64:65], 0, v[40:41]
	global_load_dwordx4 v[64:67], v[42:43], off
	v_lshl_add_u64 v[44:45], s[36:37], 0, v[40:41]
	global_load_dwordx4 v[68:71], v[44:45], off
	v_lshl_add_u64 v[40:41], s[16:17], 0, v[40:41]
	global_load_dwordx4 v[60:63], v[40:41], off
	global_load_dwordx4 v[48:51], v[42:43], off offset:16
	s_nop 0
	global_load_dwordx4 v[44:47], v[44:45], off offset:16
	s_nop 0
	global_load_dwordx4 v[40:43], v[40:41], off offset:16
	v_or_b32_e32 v92, 16, v72
	v_or_b32_e32 v94, 32, v72
	v_or_b32_e32 v112, 48, v72
	v_add_u32_e32 v114, 0x80, v72
	v_add_u32_e32 v132, 0x90, v72
	v_add_u32_e32 v134, 0xa0, v72
	v_add_u32_e32 v72, 0xb0, v72
	v_ashrrev_i32_e32 v93, 31, v92
	v_ashrrev_i32_e32 v95, 31, v94
	v_ashrrev_i32_e32 v113, 31, v112
	v_ashrrev_i32_e32 v115, 31, v114
	v_ashrrev_i32_e32 v133, 31, v132
	v_ashrrev_i32_e32 v135, 31, v134
	v_ashrrev_i32_e32 v73, 31, v72
	v_lshlrev_b64 v[92:93], 13, v[92:93]
	v_lshlrev_b64 v[94:95], 13, v[94:95]
	v_lshlrev_b64 v[112:113], 13, v[112:113]
	v_lshlrev_b64 v[114:115], 13, v[114:115]
	v_lshlrev_b64 v[132:133], 13, v[132:133]
	v_lshlrev_b64 v[134:135], 13, v[134:135]
	v_lshlrev_b64 v[72:73], 13, v[72:73]
	v_lshl_add_u64 v[92:93], v[74:75], 0, v[92:93]
	v_lshl_add_u64 v[94:95], v[74:75], 0, v[94:95]
	v_lshl_add_u64 v[112:113], v[74:75], 0, v[112:113]
	v_lshl_add_u64 v[114:115], v[74:75], 0, v[114:115]
	v_lshl_add_u64 v[206:207], v[74:75], 0, v[132:133]
	v_lshl_add_u64 v[208:209], v[74:75], 0, v[134:135]
	v_lshl_add_u64 v[72:73], v[74:75], 0, v[72:73]
	global_load_dwordx4 v[176:179], v[92:93], off nt
	global_load_dwordx4 v[172:175], v[94:95], off nt
	global_load_dwordx4 v[152:155], v[112:113], off nt
	global_load_dwordx4 v[132:135], v[114:115], off nt
	s_nop 0
	global_load_dwordx4 v[112:115], v[206:207], off nt
	global_load_dwordx4 v[92:95], v[208:209], off nt
	s_nop 0
	global_load_dwordx4 v[72:75], v[72:73], off nt
	s_lshl_b32 s0, s0, 6
	s_add_i32 s44, s0, s1
	s_ashr_i32 s45, s44, 31
	s_lshl_b64 s[0:1], s[44:45], 14
	v_mov_b32_e32 v205, s1
	v_or_b32_e32 v204, s0, v190
	s_waitcnt vmcnt(0)
	v_lshlrev_b32_e32 v208, 16, v218
	v_and_b32_e32 v209, 0xffff0000, v218
	v_pk_add_f32 v[168:169], v[168:169], v[64:65]
	v_lshlrev_b32_e32 v206, 16, v219
	v_pk_mul_f32 v[168:169], v[168:169], s[24:25] op_sel_hi:[1,0]
	v_pk_add_f32 v[164:165], v[164:165], v[68:69]
	v_exp_f32_e32 v168, v168
	v_exp_f32_e32 v169, v169
	v_pk_mul_f32 v[164:165], v[164:165], s[24:25] op_sel_hi:[1,0]
	v_and_b32_e32 v207, 0xffff0000, v219
	v_exp_f32_e32 v218, v164
	v_pk_add_f32 v[168:169], v[168:169], 1.0 op_sel_hi:[1,0]
	v_exp_f32_e32 v219, v165
	v_rcp_f32_e32 v168, v168
	v_rcp_f32_e32 v169, v169
	v_pk_add_f32 v[222:223], v[166:167], v[70:71]
	v_pk_add_f32 v[166:167], v[218:219], 1.0 op_sel_hi:[1,0]
	v_pk_add_f32 v[170:171], v[170:171], v[66:67]
	v_pk_mul_f32 v[164:165], v[60:61], v[168:169] neg_lo:[1,0] neg_hi:[1,0]
	v_pk_mul_f32 v[170:171], v[170:171], s[24:25] op_sel_hi:[1,0]
	v_pk_mul_f32 v[168:169], v[164:165], s[26:27] op_sel_hi:[1,0]
	v_rcp_f32_e32 v166, v166
	v_exp_f32_e32 v168, v168
	v_exp_f32_e32 v169, v169
	v_rcp_f32_e32 v167, v167
	v_exp_f32_e32 v170, v170
	v_exp_f32_e32 v171, v171
	v_pk_add_f32 v[168:169], v[168:169], 1.0 op_sel_hi:[1,0] neg_lo:[1,0] neg_hi:[1,0]
	v_xor_b32_e32 v62, 0x80000000, v62
	v_max_f32_e32 v168, 0, v168
	v_max_f32_e32 v169, 0, v169
	v_xor_b32_e32 v63, 0x80000000, v63
	v_lshlrev_b32_e32 v220, 16, v216
	v_and_b32_e32 v221, 0xffff0000, v216
	v_pk_add_f32 v[160:161], v[160:161], v[48:49]
	v_pk_mul_f32 v[160:161], v[160:161], s[24:25] op_sel_hi:[1,0]
	v_lshlrev_b32_e32 v216, 16, v217
	v_sqrt_f32_e32 v168, v168
	v_exp_f32_e32 v160, v160
	v_exp_f32_e32 v161, v161
	v_pk_mul_f32 v[218:219], v[222:223], s[24:25] op_sel_hi:[1,0]
	v_pk_add_f32 v[160:161], v[160:161], 1.0 op_sel_hi:[1,0]
	v_sqrt_f32_e32 v169, v169
	s_nop 0
	v_pk_mul_f32 v[166:167], v[166:167], v[168:169]
	v_pk_add_f32 v[168:169], v[170:171], 1.0 op_sel_hi:[1,0]
	v_pk_mul_f32 v[166:167], v[166:167], v[220:221]
	v_rcp_f32_e32 v168, v168
	v_rcp_f32_e32 v169, v169
	v_exp_f32_e32 v218, v218
	v_exp_f32_e32 v219, v219
	v_rcp_f32_e32 v160, v160
	v_pk_mul_f32 v[168:169], v[62:63], v[168:169]
	v_rcp_f32_e32 v161, v161
	v_pk_mul_f32 v[170:171], v[168:169], s[26:27] op_sel_hi:[1,0]
	v_pk_add_f32 v[218:219], v[218:219], 1.0 op_sel_hi:[1,0]
	v_exp_f32_e32 v170, v170
	v_exp_f32_e32 v171, v171
	v_rcp_f32_e32 v218, v218
	v_rcp_f32_e32 v219, v219
	v_and_b32_e32 v217, 0xffff0000, v217
	v_pk_add_f32 v[170:171], v[170:171], 1.0 op_sel_hi:[1,0] neg_lo:[1,0] neg_hi:[1,0]
	v_pk_mul_f32 v[160:161], v[40:41], v[160:161] neg_lo:[1,0] neg_hi:[1,0]
	v_max_f32_e32 v170, 0, v170
	v_max_f32_e32 v171, 0, v171
	v_pk_add_f32 v[162:163], v[162:163], v[50:51]
	v_pk_add_f32 v[156:157], v[156:157], v[44:45]
	v_pk_mul_f32 v[162:163], v[162:163], s[24:25] op_sel_hi:[1,0]
	v_pk_mul_f32 v[156:157], v[156:157], s[24:25] op_sel_hi:[1,0]
	v_exp_f32_e32 v156, v156
	v_exp_f32_e32 v157, v157
	v_exp_f32_e32 v162, v162
	v_exp_f32_e32 v163, v163
	v_pk_add_f32 v[156:157], v[156:157], 1.0 op_sel_hi:[1,0]
	v_sqrt_f32_e32 v170, v170
	v_pk_add_f32 v[162:163], v[162:163], 1.0 op_sel_hi:[1,0]
	v_rcp_f32_e32 v156, v156
	v_rcp_f32_e32 v157, v157
	v_rcp_f32_e32 v162, v162
	v_rcp_f32_e32 v163, v163
	v_sqrt_f32_e32 v171, v171
	s_nop 0
	v_pk_mul_f32 v[170:171], v[218:219], v[170:171]
	v_xor_b32_e32 v42, 0x80000000, v42
	v_pk_mul_f32 v[170:171], v[170:171], v[216:217]
	v_pk_mul_f32 v[216:217], v[160:161], s[26:27] op_sel_hi:[1,0]
	v_xor_b32_e32 v43, 0x80000000, v43
	v_exp_f32_e32 v216, v216
	v_exp_f32_e32 v217, v217
	v_pk_mul_f32 v[162:163], v[42:43], v[162:163]
	v_pk_add_f32 v[158:159], v[158:159], v[46:47]
	v_pk_add_f32 v[148:149], v[148:149], v[64:65]
	v_pk_add_f32 v[216:217], v[216:217], 1.0 op_sel_hi:[1,0] neg_lo:[1,0] neg_hi:[1,0]
	v_pk_mul_f32 v[158:159], v[158:159], s[24:25] op_sel_hi:[1,0]
	v_max_f32_e32 v215, 0, v216
	v_max_f32_e32 v217, 0, v217
	v_exp_f32_e32 v158, v158
	v_exp_f32_e32 v159, v159
	v_pk_mul_f32 v[148:149], v[148:149], s[24:25] op_sel_hi:[1,0]
	v_pk_add_f32 v[150:151], v[150:151], v[66:67]
	v_pk_add_f32 v[158:159], v[158:159], 1.0 op_sel_hi:[1,0]
	v_rcp_f32_e32 v158, v158
	v_rcp_f32_e32 v159, v159
	v_pk_mul_f32 v[150:151], v[150:151], s[24:25] op_sel_hi:[1,0]
	v_pk_add_f32 v[140:141], v[140:141], v[48:49]
	v_sqrt_f32_e32 v216, v215
	v_exp_f32_e32 v150, v150
	v_exp_f32_e32 v151, v151
	v_pk_mul_f32 v[140:141], v[140:141], s[24:25] op_sel_hi:[1,0]
	v_pk_add_f32 v[150:151], v[150:151], 1.0 op_sel_hi:[1,0]
	v_exp_f32_e32 v140, v140
	v_sqrt_f32_e32 v217, v217
	s_nop 0
	v_pk_mul_f32 v[156:157], v[156:157], v[216:217]
	v_rcp_f32_e32 v150, v150
	v_pk_mul_f32 v[208:209], v[156:157], v[208:209]
	v_pk_mul_f32 v[156:157], v[162:163], s[26:27] op_sel_hi:[1,0]
	v_rcp_f32_e32 v151, v151
	v_exp_f32_e32 v156, v156
	v_exp_f32_e32 v157, v157
	v_exp_f32_e32 v141, v141
	v_pk_mul_f32 v[150:151], v[62:63], v[150:151]
	v_pk_add_f32 v[142:143], v[142:143], v[50:51]
	v_pk_add_f32 v[156:157], v[156:157], 1.0 op_sel_hi:[1,0] neg_lo:[1,0] neg_hi:[1,0]
	v_pk_add_f32 v[140:141], v[140:141], 1.0 op_sel_hi:[1,0]
	v_max_f32_e32 v156, 0, v156
	v_max_f32_e32 v157, 0, v157
	v_rcp_f32_e32 v140, v140
	v_rcp_f32_e32 v141, v141
	v_pk_add_f32 v[136:137], v[136:137], v[44:45]
	v_pk_mul_f32 v[142:143], v[142:143], s[24:25] op_sel_hi:[1,0]
	v_pk_mul_f32 v[140:141], v[40:41], v[140:141] neg_lo:[1,0] neg_hi:[1,0]
	v_pk_mul_f32 v[136:137], v[136:137], s[24:25] op_sel_hi:[1,0]
	v_exp_f32_e32 v142, v142
	v_exp_f32_e32 v136, v136
	v_exp_f32_e32 v137, v137
	v_sqrt_f32_e32 v156, v156
	v_exp_f32_e32 v143, v143
	v_pk_add_f32 v[136:137], v[136:137], 1.0 op_sel_hi:[1,0]
	v_pk_add_f32 v[142:143], v[142:143], 1.0 op_sel_hi:[1,0]
	v_rcp_f32_e32 v136, v136
	v_rcp_f32_e32 v137, v137
	v_sqrt_f32_e32 v157, v157
	s_nop 0
	v_pk_mul_f32 v[156:157], v[158:159], v[156:157]
	v_cvt_pk_bf16_f32 v158, v160, v161
	v_cvt_pk_bf16_f32 v160, v166, v167
	v_cvt_pk_bf16_f32 v159, v162, v163
	v_cvt_pk_bf16_f32 v162, v208, v209
	v_cvt_pk_bf16_f32 v161, v170, v171
	s_nop 0
	v_pk_mul_f32 v[206:207], v[156:157], v[206:207]
	v_cvt_pk_bf16_f32 v156, v164, v165
	v_lshl_add_u64 v[164:165], v[204:205], 0, v[192:193]
	v_lshlrev_b64 v[164:165], 1, v[164:165]
	v_cvt_pk_bf16_f32 v157, v168, v169
	v_lshl_add_u64 v[166:167], s[18:19], 0, v[164:165]
	v_cvt_pk_bf16_f32 v163, v206, v207
	global_store_dwordx4 v[166:167], v[156:159], off
	v_rcp_f32_e32 v142, v142
	v_rcp_f32_e32 v143, v143
	v_lshl_add_u64 v[156:157], s[20:21], 0, v[164:165]
	global_store_dwordx4 v[156:157], v[160:163], off
	v_pk_add_f32 v[164:165], v[146:147], v[70:71]
	v_pk_add_f32 v[146:147], v[144:145], v[68:69]
	v_exp_f32_e32 v162, v148
	v_exp_f32_e32 v163, v149
	v_pk_mul_f32 v[146:147], v[146:147], s[24:25] op_sel_hi:[1,0]
	v_lshlrev_b32_e32 v158, 16, v176
	v_exp_f32_e32 v146, v146
	v_pk_add_f32 v[162:163], v[162:163], 1.0 op_sel_hi:[1,0]
	v_exp_f32_e32 v147, v147
	v_rcp_f32_e32 v162, v162
	v_rcp_f32_e32 v163, v163
	v_and_b32_e32 v159, 0xffff0000, v176
	v_pk_add_f32 v[146:147], v[146:147], 1.0 op_sel_hi:[1,0]
	v_lshlrev_b32_e32 v160, 16, v177
	v_pk_mul_f32 v[144:145], v[60:61], v[162:163] neg_lo:[1,0] neg_hi:[1,0]
	v_rcp_f32_e32 v146, v146
	v_pk_mul_f32 v[162:163], v[144:145], s[26:27] op_sel_hi:[1,0]
	v_rcp_f32_e32 v147, v147
	v_exp_f32_e32 v162, v162
	v_exp_f32_e32 v163, v163
	v_and_b32_e32 v161, 0xffff0000, v177
	v_lshlrev_b32_e32 v156, 16, v178
	v_and_b32_e32 v157, 0xffff0000, v178
	v_pk_add_f32 v[162:163], v[162:163], 1.0 op_sel_hi:[1,0] neg_lo:[1,0] neg_hi:[1,0]
	v_pk_mul_f32 v[142:143], v[42:43], v[142:143]
	v_max_f32_e32 v162, 0, v162
	v_max_f32_e32 v163, 0, v163
	v_pk_add_f32 v[138:139], v[138:139], v[46:47]
	v_pk_mul_f32 v[138:139], v[138:139], s[24:25] op_sel_hi:[1,0]
	v_lshlrev_b32_e32 v148, 16, v179
	v_exp_f32_e32 v138, v138
	v_exp_f32_e32 v139, v139
	s_nop 0
	v_pk_add_f32 v[138:139], v[138:139], 1.0 op_sel_hi:[1,0]
	v_and_b32_e32 v149, 0xffff0000, v179
	v_rcp_f32_e32 v138, v138
	v_rcp_f32_e32 v139, v139
	v_sqrt_f32_e32 v162, v162
	v_pk_add_f32 v[128:129], v[128:129], v[64:65]
	v_pk_mul_f32 v[128:129], v[128:129], s[24:25] op_sel_hi:[1,0]
	v_pk_add_f32 v[130:131], v[130:131], v[66:67]
	v_pk_mul_f32 v[130:131], v[130:131], s[24:25] op_sel_hi:[1,0]
	v_pk_add_f32 v[120:121], v[120:121], v[48:49]
	v_sqrt_f32_e32 v163, v163
	s_nop 0
	v_pk_mul_f32 v[146:147], v[146:147], v[162:163]
	v_pk_mul_f32 v[162:163], v[164:165], s[24:25] op_sel_hi:[1,0]
	v_pk_mul_f32 v[146:147], v[146:147], v[158:159]
	v_pk_mul_f32 v[158:159], v[150:151], s[26:27] op_sel_hi:[1,0]
	v_exp_f32_e32 v162, v162
	v_exp_f32_e32 v158, v158
	v_exp_f32_e32 v159, v159
	v_exp_f32_e32 v163, v163
	v_exp_f32_e32 v130, v130
	v_exp_f32_e32 v131, v131
	v_pk_add_f32 v[158:159], v[158:159], 1.0 op_sel_hi:[1,0] neg_lo:[1,0] neg_hi:[1,0]
	v_pk_add_f32 v[162:163], v[162:163], 1.0 op_sel_hi:[1,0]
	v_max_f32_e32 v158, 0, v158
	v_max_f32_e32 v159, 0, v159
	v_rcp_f32_e32 v162, v162
	v_rcp_f32_e32 v163, v163
	v_pk_add_f32 v[130:131], v[130:131], 1.0 op_sel_hi:[1,0]
	v_pk_mul_f32 v[120:121], v[120:121], s[24:25] op_sel_hi:[1,0]
	v_rcp_f32_e32 v130, v130
	v_rcp_f32_e32 v131, v131
	v_exp_f32_e32 v120, v120
	v_pk_mul_f32 v[130:131], v[62:63], v[130:131]
	v_exp_f32_e32 v121, v121
	v_sqrt_f32_e32 v158, v158
	v_pk_add_f32 v[120:121], v[120:121], 1.0 op_sel_hi:[1,0]
	v_rcp_f32_e32 v120, v120
	v_rcp_f32_e32 v121, v121
	s_nop 0
	v_pk_mul_f32 v[120:121], v[40:41], v[120:121] neg_lo:[1,0] neg_hi:[1,0]
	v_pk_add_f32 v[122:123], v[122:123], v[50:51]
	v_sqrt_f32_e32 v159, v159
	s_nop 0
	v_pk_mul_f32 v[158:159], v[162:163], v[158:159]
	v_pk_add_f32 v[116:117], v[116:117], v[44:45]
	v_pk_mul_f32 v[158:159], v[158:159], v[160:161]
	v_pk_mul_f32 v[160:161], v[140:141], s[26:27] op_sel_hi:[1,0]
	v_pk_mul_f32 v[116:117], v[116:117], s[24:25] op_sel_hi:[1,0]
	v_exp_f32_e32 v160, v160
	v_exp_f32_e32 v161, v161
	v_pk_mul_f32 v[122:123], v[122:123], s[24:25] op_sel_hi:[1,0]
	v_exp_f32_e32 v116, v116
	v_exp_f32_e32 v117, v117
	v_pk_add_f32 v[160:161], v[160:161], 1.0 op_sel_hi:[1,0] neg_lo:[1,0] neg_hi:[1,0]
	v_exp_f32_e32 v122, v122
	v_max_f32_e32 v160, 0, v160
	v_max_f32_e32 v161, 0, v161
	v_exp_f32_e32 v123, v123
	v_pk_add_f32 v[116:117], v[116:117], 1.0 op_sel_hi:[1,0]
	v_pk_add_f32 v[122:123], v[122:123], 1.0 op_sel_hi:[1,0]
	v_rcp_f32_e32 v116, v116
	v_rcp_f32_e32 v117, v117
	v_rcp_f32_e32 v122, v122
	v_rcp_f32_e32 v123, v123
	s_nop 0
	v_pk_mul_f32 v[122:123], v[42:43], v[122:123]
	v_pk_add_f32 v[118:119], v[118:119], v[46:47]
	v_sqrt_f32_e32 v160, v160
	v_pk_mul_f32 v[118:119], v[118:119], s[24:25] op_sel_hi:[1,0]
	v_exp_f32_e32 v118, v118
	v_exp_f32_e32 v119, v119
	s_nop 0
	v_pk_add_f32 v[118:119], v[118:119], 1.0 op_sel_hi:[1,0]
	v_pk_add_f32 v[108:109], v[108:109], v[64:65]
	v_sqrt_f32_e32 v161, v161
	s_nop 0
	v_pk_mul_f32 v[136:137], v[136:137], v[160:161]
	v_rcp_f32_e32 v118, v118
	v_pk_mul_f32 v[156:157], v[136:137], v[156:157]
	v_pk_mul_f32 v[136:137], v[142:143], s[26:27] op_sel_hi:[1,0]
	v_rcp_f32_e32 v119, v119
	v_exp_f32_e32 v136, v136
	v_exp_f32_e32 v137, v137
	v_pk_mul_f32 v[108:109], v[108:109], s[24:25] op_sel_hi:[1,0]
	v_pk_add_f32 v[110:111], v[110:111], v[66:67]
	v_pk_add_f32 v[100:101], v[100:101], v[48:49]
	v_pk_add_f32 v[136:137], v[136:137], 1.0 op_sel_hi:[1,0] neg_lo:[1,0] neg_hi:[1,0]
	v_pk_mul_f32 v[110:111], v[110:111], s[24:25] op_sel_hi:[1,0]
	v_max_f32_e32 v136, 0, v136
	v_max_f32_e32 v137, 0, v137
	v_exp_f32_e32 v110, v110
	v_exp_f32_e32 v111, v111
	v_pk_mul_f32 v[100:101], v[100:101], s[24:25] op_sel_hi:[1,0]
	v_pk_add_f32 v[102:103], v[102:103], v[50:51]
	v_pk_add_f32 v[110:111], v[110:111], 1.0 op_sel_hi:[1,0]
	v_rcp_f32_e32 v110, v110
	v_rcp_f32_e32 v111, v111
	s_nop 0
	v_pk_mul_f32 v[110:111], v[62:63], v[110:111]
	v_exp_f32_e32 v100, v100
	v_sqrt_f32_e32 v136, v136
	v_exp_f32_e32 v101, v101
	s_nop 0
	v_pk_add_f32 v[100:101], v[100:101], 1.0 op_sel_hi:[1,0]
	v_pk_add_f32 v[96:97], v[96:97], v[44:45]
	v_rcp_f32_e32 v100, v100
	v_rcp_f32_e32 v101, v101
	v_sqrt_f32_e32 v137, v137
	s_nop 0
	v_pk_mul_f32 v[136:137], v[138:139], v[136:137]
	v_cvt_pk_bf16_f32 v138, v140, v141
	v_cvt_pk_bf16_f32 v140, v146, v147
	v_cvt_pk_bf16_f32 v139, v142, v143
	v_cvt_pk_bf16_f32 v142, v156, v157
	v_cvt_pk_bf16_f32 v141, v158, v159
	s_nop 0
	v_pk_mul_f32 v[148:149], v[136:137], v[148:149]
	v_cvt_pk_bf16_f32 v136, v144, v145
	v_lshl_add_u64 v[144:145], v[204:205], 0, v[194:195]
	v_lshlrev_b64 v[144:145], 1, v[144:145]
	v_cvt_pk_bf16_f32 v137, v150, v151
	v_lshl_add_u64 v[146:147], s[18:19], 0, v[144:145]
	v_cvt_pk_bf16_f32 v143, v148, v149
	global_store_dwordx4 v[146:147], v[136:139], off
	v_pk_mul_f32 v[100:101], v[40:41], v[100:101] neg_lo:[1,0] neg_hi:[1,0]
	v_pk_mul_f32 v[96:97], v[96:97], s[24:25] op_sel_hi:[1,0]
	v_lshl_add_u64 v[136:137], s[20:21], 0, v[144:145]
	global_store_dwordx4 v[136:137], v[140:143], off
	v_pk_add_f32 v[144:145], v[126:127], v[70:71]
	v_pk_add_f32 v[126:127], v[124:125], v[68:69]
	v_exp_f32_e32 v142, v128
	v_exp_f32_e32 v143, v129
	v_pk_mul_f32 v[126:127], v[126:127], s[24:25] op_sel_hi:[1,0]
	v_lshlrev_b32_e32 v138, 16, v172
	v_exp_f32_e32 v126, v126
	v_pk_add_f32 v[142:143], v[142:143], 1.0 op_sel_hi:[1,0]
	v_exp_f32_e32 v127, v127
	v_rcp_f32_e32 v142, v142
	v_rcp_f32_e32 v143, v143
	v_and_b32_e32 v139, 0xffff0000, v172
	v_pk_add_f32 v[126:127], v[126:127], 1.0 op_sel_hi:[1,0]
	v_lshlrev_b32_e32 v140, 16, v173
	v_pk_mul_f32 v[124:125], v[60:61], v[142:143] neg_lo:[1,0] neg_hi:[1,0]
	v_rcp_f32_e32 v126, v126
	v_pk_mul_f32 v[142:143], v[124:125], s[26:27] op_sel_hi:[1,0]
	v_rcp_f32_e32 v127, v127
	v_exp_f32_e32 v142, v142
	v_exp_f32_e32 v143, v143
	v_and_b32_e32 v141, 0xffff0000, v173
	v_lshlrev_b32_e32 v136, 16, v174
	v_and_b32_e32 v137, 0xffff0000, v174
	v_pk_add_f32 v[142:143], v[142:143], 1.0 op_sel_hi:[1,0] neg_lo:[1,0] neg_hi:[1,0]
	v_lshlrev_b32_e32 v128, 16, v175
	v_max_f32_e32 v142, 0, v142
	v_max_f32_e32 v143, 0, v143
	v_and_b32_e32 v129, 0xffff0000, v175
	v_pk_mul_f32 v[102:103], v[102:103], s[24:25] op_sel_hi:[1,0]
	v_exp_f32_e32 v96, v96
	v_exp_f32_e32 v97, v97
	v_exp_f32_e32 v102, v102
	v_exp_f32_e32 v103, v103
	v_pk_add_f32 v[96:97], v[96:97], 1.0 op_sel_hi:[1,0]
	v_pk_add_f32 v[102:103], v[102:103], 1.0 op_sel_hi:[1,0]
	v_rcp_f32_e32 v96, v96
	v_sqrt_f32_e32 v142, v142
	v_rcp_f32_e32 v97, v97
	v_rcp_f32_e32 v102, v102
	v_rcp_f32_e32 v103, v103
	s_nop 0
	v_pk_mul_f32 v[102:103], v[42:43], v[102:103]
	v_pk_add_f32 v[98:99], v[98:99], v[46:47]
	v_sqrt_f32_e32 v143, v143
	s_nop 0
	v_pk_mul_f32 v[126:127], v[126:127], v[142:143]
	v_pk_mul_f32 v[142:143], v[144:145], s[24:25] op_sel_hi:[1,0]
	v_pk_mul_f32 v[126:127], v[126:127], v[138:139]
	v_pk_mul_f32 v[138:139], v[130:131], s[26:27] op_sel_hi:[1,0]
	v_exp_f32_e32 v142, v142
	v_exp_f32_e32 v138, v138
	v_exp_f32_e32 v139, v139
	v_exp_f32_e32 v143, v143
	v_pk_mul_f32 v[98:99], v[98:99], s[24:25] op_sel_hi:[1,0]
	v_pk_add_f32 v[88:89], v[88:89], v[64:65]
	v_pk_add_f32 v[138:139], v[138:139], 1.0 op_sel_hi:[1,0] neg_lo:[1,0] neg_hi:[1,0]
	v_pk_add_f32 v[142:143], v[142:143], 1.0 op_sel_hi:[1,0]
	v_max_f32_e32 v138, 0, v138
	v_max_f32_e32 v139, 0, v139
	v_rcp_f32_e32 v142, v142
	v_rcp_f32_e32 v143, v143
	v_exp_f32_e32 v98, v98
	v_exp_f32_e32 v99, v99
	s_nop 0
	v_pk_add_f32 v[98:99], v[98:99], 1.0 op_sel_hi:[1,0]
	v_rcp_f32_e32 v98, v98
	v_rcp_f32_e32 v99, v99
	v_pk_mul_f32 v[88:89], v[88:89], s[24:25] op_sel_hi:[1,0]
	v_pk_add_f32 v[90:91], v[90:91], v[66:67]
	v_sqrt_f32_e32 v138, v138
	v_pk_mul_f32 v[90:91], v[90:91], s[24:25] op_sel_hi:[1,0]
	v_exp_f32_e32 v90, v90
	v_exp_f32_e32 v91, v91
	s_nop 0
	v_pk_add_f32 v[90:91], v[90:91], 1.0 op_sel_hi:[1,0]
	v_pk_add_f32 v[80:81], v[80:81], v[48:49]
	v_sqrt_f32_e32 v139, v139
	s_nop 0
	v_pk_mul_f32 v[138:139], v[142:143], v[138:139]
	v_rcp_f32_e32 v90, v90
	v_pk_mul_f32 v[138:139], v[138:139], v[140:141]
	v_pk_mul_f32 v[140:141], v[120:121], s[26:27] op_sel_hi:[1,0]
	v_rcp_f32_e32 v91, v91
	v_exp_f32_e32 v140, v140
	v_exp_f32_e32 v141, v141
	v_pk_mul_f32 v[80:81], v[80:81], s[24:25] op_sel_hi:[1,0]
	v_pk_mul_f32 v[90:91], v[62:63], v[90:91]
	v_exp_f32_e32 v80, v80
	v_pk_add_f32 v[140:141], v[140:141], 1.0 op_sel_hi:[1,0] neg_lo:[1,0] neg_hi:[1,0]
	v_exp_f32_e32 v81, v81
	v_max_f32_e32 v140, 0, v140
	v_max_f32_e32 v141, 0, v141
	v_pk_add_f32 v[80:81], v[80:81], 1.0 op_sel_hi:[1,0]
	v_rcp_f32_e32 v80, v80
	v_rcp_f32_e32 v81, v81
	v_pk_add_f32 v[82:83], v[82:83], v[50:51]
	v_pk_mul_f32 v[80:81], v[40:41], v[80:81] neg_lo:[1,0] neg_hi:[1,0]
	v_pk_add_f32 v[76:77], v[76:77], v[44:45]
	v_pk_mul_f32 v[82:83], v[82:83], s[24:25] op_sel_hi:[1,0]
	v_pk_mul_f32 v[76:77], v[76:77], s[24:25] op_sel_hi:[1,0]
	v_exp_f32_e32 v82, v82
	v_sqrt_f32_e32 v140, v140
	v_exp_f32_e32 v76, v76
	v_exp_f32_e32 v77, v77
	v_exp_f32_e32 v83, v83
	v_pk_add_f32 v[76:77], v[76:77], 1.0 op_sel_hi:[1,0]
	v_pk_add_f32 v[82:83], v[82:83], 1.0 op_sel_hi:[1,0]
	v_sqrt_f32_e32 v141, v141
	s_nop 0
	v_pk_mul_f32 v[116:117], v[116:117], v[140:141]
	v_rcp_f32_e32 v76, v76
	v_pk_mul_f32 v[136:137], v[116:117], v[136:137]
	v_pk_mul_f32 v[116:117], v[122:123], s[26:27] op_sel_hi:[1,0]
	v_rcp_f32_e32 v77, v77
	v_exp_f32_e32 v116, v116
	v_exp_f32_e32 v117, v117
	v_rcp_f32_e32 v82, v82
	v_rcp_f32_e32 v83, v83
	v_pk_add_f32 v[78:79], v[78:79], v[46:47]
	v_pk_add_f32 v[116:117], v[116:117], 1.0 op_sel_hi:[1,0] neg_lo:[1,0] neg_hi:[1,0]
	v_pk_mul_f32 v[78:79], v[78:79], s[24:25] op_sel_hi:[1,0]
	v_max_f32_e32 v116, 0, v116
	v_max_f32_e32 v117, 0, v117
	v_pk_mul_f32 v[82:83], v[42:43], v[82:83]
	v_exp_f32_e32 v78, v78
	v_exp_f32_e32 v79, v79
	v_pk_add_f32 v[56:57], v[56:57], v[64:65]
	v_pk_add_f32 v[78:79], v[78:79], 1.0 op_sel_hi:[1,0]
	v_rcp_f32_e32 v78, v78
	v_rcp_f32_e32 v79, v79
	v_pk_mul_f32 v[56:57], v[56:57], s[24:25] op_sel_hi:[1,0]
	v_pk_add_f32 v[58:59], v[58:59], v[66:67]
	v_sqrt_f32_e32 v116, v116
	v_pk_mul_f32 v[58:59], v[58:59], s[24:25] op_sel_hi:[1,0]
	v_exp_f32_e32 v58, v58
	v_exp_f32_e32 v59, v59
	s_nop 0
	v_pk_add_f32 v[58:59], v[58:59], 1.0 op_sel_hi:[1,0]
	v_pk_add_f32 v[36:37], v[36:37], v[48:49]
	v_sqrt_f32_e32 v117, v117
	s_nop 0
	v_pk_mul_f32 v[116:117], v[118:119], v[116:117]
	v_cvt_pk_bf16_f32 v118, v120, v121
	v_cvt_pk_bf16_f32 v120, v126, v127
	v_cvt_pk_bf16_f32 v119, v122, v123
	v_cvt_pk_bf16_f32 v122, v136, v137
	v_cvt_pk_bf16_f32 v121, v138, v139
	s_nop 0
	v_pk_mul_f32 v[128:129], v[116:117], v[128:129]
	v_cvt_pk_bf16_f32 v116, v124, v125
	v_lshl_add_u64 v[124:125], v[204:205], 0, v[196:197]
	v_lshlrev_b64 v[124:125], 1, v[124:125]
	v_cvt_pk_bf16_f32 v117, v130, v131
	v_lshl_add_u64 v[126:127], s[18:19], 0, v[124:125]
	v_cvt_pk_bf16_f32 v123, v128, v129
	global_store_dwordx4 v[126:127], v[116:119], off
	v_rcp_f32_e32 v58, v58
	v_rcp_f32_e32 v59, v59
	v_lshl_add_u64 v[116:117], s[20:21], 0, v[124:125]
	global_store_dwordx4 v[116:117], v[120:123], off
	v_pk_add_f32 v[124:125], v[106:107], v[70:71]
	v_pk_add_f32 v[106:107], v[104:105], v[68:69]
	v_exp_f32_e32 v122, v108
	v_exp_f32_e32 v123, v109
	v_pk_mul_f32 v[106:107], v[106:107], s[24:25] op_sel_hi:[1,0]
	v_lshlrev_b32_e32 v118, 16, v152
	v_exp_f32_e32 v106, v106
	v_pk_add_f32 v[122:123], v[122:123], 1.0 op_sel_hi:[1,0]
	v_exp_f32_e32 v107, v107
	v_rcp_f32_e32 v122, v122
	v_rcp_f32_e32 v123, v123
	v_and_b32_e32 v119, 0xffff0000, v152
	v_pk_add_f32 v[106:107], v[106:107], 1.0 op_sel_hi:[1,0]
	v_lshlrev_b32_e32 v120, 16, v153
	v_pk_mul_f32 v[104:105], v[60:61], v[122:123] neg_lo:[1,0] neg_hi:[1,0]
	v_rcp_f32_e32 v106, v106
	v_pk_mul_f32 v[122:123], v[104:105], s[26:27] op_sel_hi:[1,0]
	v_rcp_f32_e32 v107, v107
	v_exp_f32_e32 v122, v122
	v_exp_f32_e32 v123, v123
	v_and_b32_e32 v121, 0xffff0000, v153
	v_lshlrev_b32_e32 v116, 16, v154
	v_and_b32_e32 v117, 0xffff0000, v154
	v_pk_add_f32 v[122:123], v[122:123], 1.0 op_sel_hi:[1,0] neg_lo:[1,0] neg_hi:[1,0]
	v_lshlrev_b32_e32 v108, 16, v155
	v_max_f32_e32 v122, 0, v122
	v_max_f32_e32 v123, 0, v123
	v_and_b32_e32 v109, 0xffff0000, v155
	v_pk_mul_f32 v[58:59], v[62:63], v[58:59]
	v_pk_mul_f32 v[36:37], v[36:37], s[24:25] op_sel_hi:[1,0]
	v_pk_add_f32 v[38:39], v[38:39], v[50:51]
	v_exp_f32_e32 v36, v36
	v_exp_f32_e32 v37, v37
	v_pk_add_f32 v[32:33], v[32:33], v[44:45]
	v_pk_add_f32 v[36:37], v[36:37], 1.0 op_sel_hi:[1,0]
	v_pk_mul_f32 v[32:33], v[32:33], s[24:25] op_sel_hi:[1,0]
	v_sqrt_f32_e32 v122, v122
	v_rcp_f32_e32 v36, v36
	v_rcp_f32_e32 v37, v37
	v_pk_mul_f32 v[38:39], v[38:39], s[24:25] op_sel_hi:[1,0]
	v_pk_mul_f32 v[36:37], v[40:41], v[36:37] neg_lo:[1,0] neg_hi:[1,0]
	v_exp_f32_e32 v32, v32
	v_sqrt_f32_e32 v123, v123
	s_nop 0
	v_pk_mul_f32 v[106:107], v[106:107], v[122:123]
	v_pk_mul_f32 v[122:123], v[124:125], s[24:25] op_sel_hi:[1,0]
	v_pk_mul_f32 v[106:107], v[106:107], v[118:119]
	v_pk_mul_f32 v[118:119], v[110:111], s[26:27] op_sel_hi:[1,0]
	v_exp_f32_e32 v122, v122
	v_exp_f32_e32 v118, v118
	v_exp_f32_e32 v119, v119
	v_exp_f32_e32 v123, v123
	v_exp_f32_e32 v33, v33
	v_exp_f32_e32 v38, v38
	v_pk_add_f32 v[118:119], v[118:119], 1.0 op_sel_hi:[1,0] neg_lo:[1,0] neg_hi:[1,0]
	v_pk_add_f32 v[122:123], v[122:123], 1.0 op_sel_hi:[1,0]
	v_max_f32_e32 v118, 0, v118
	v_max_f32_e32 v119, 0, v119
	v_rcp_f32_e32 v122, v122
	v_rcp_f32_e32 v123, v123
	v_exp_f32_e32 v39, v39
	v_pk_add_f32 v[32:33], v[32:33], 1.0 op_sel_hi:[1,0]
	v_pk_add_f32 v[38:39], v[38:39], 1.0 op_sel_hi:[1,0]
	v_rcp_f32_e32 v32, v32
	v_rcp_f32_e32 v33, v33
	v_rcp_f32_e32 v38, v38
	v_rcp_f32_e32 v39, v39
	v_sqrt_f32_e32 v118, v118
	v_pk_mul_f32 v[38:39], v[42:43], v[38:39]
	v_pk_add_f32 v[34:35], v[34:35], v[46:47]
	v_pk_add_f32 v[28:29], v[28:29], v[64:65]
	v_pk_mul_f32 v[34:35], v[34:35], s[24:25] op_sel_hi:[1,0]
	v_pk_mul_f32 v[28:29], v[28:29], s[24:25] op_sel_hi:[1,0]
	v_sqrt_f32_e32 v119, v119
	s_nop 0
	v_pk_mul_f32 v[118:119], v[122:123], v[118:119]
	v_exp_f32_e32 v34, v34
	v_pk_mul_f32 v[118:119], v[118:119], v[120:121]
	v_pk_mul_f32 v[120:121], v[100:101], s[26:27] op_sel_hi:[1,0]
	v_exp_f32_e32 v35, v35
	v_exp_f32_e32 v120, v120
	v_exp_f32_e32 v121, v121
	v_pk_add_f32 v[30:31], v[30:31], v[66:67]
	v_pk_add_f32 v[34:35], v[34:35], 1.0 op_sel_hi:[1,0]
	v_pk_mul_f32 v[30:31], v[30:31], s[24:25] op_sel_hi:[1,0]
	v_pk_add_f32 v[120:121], v[120:121], 1.0 op_sel_hi:[1,0] neg_lo:[1,0] neg_hi:[1,0]
	v_rcp_f32_e32 v34, v34
	v_max_f32_e32 v120, 0, v120
	v_max_f32_e32 v121, 0, v121
	v_rcp_f32_e32 v35, v35
	v_exp_f32_e32 v30, v30
	v_exp_f32_e32 v31, v31
	v_pk_add_f32 v[20:21], v[20:21], v[48:49]
	v_pk_add_f32 v[30:31], v[30:31], 1.0 op_sel_hi:[1,0]
	v_rcp_f32_e32 v30, v30
	v_rcp_f32_e32 v31, v31
	s_nop 0
	v_pk_mul_f32 v[30:31], v[62:63], v[30:31]
	v_pk_mul_f32 v[20:21], v[20:21], s[24:25] op_sel_hi:[1,0]
	v_sqrt_f32_e32 v120, v120
	v_exp_f32_e32 v20, v20
	v_exp_f32_e32 v21, v21
	v_pk_add_f32 v[22:23], v[22:23], v[50:51]
	v_pk_add_f32 v[20:21], v[20:21], 1.0 op_sel_hi:[1,0]
	v_pk_add_f32 v[16:17], v[16:17], v[44:45]
	v_sqrt_f32_e32 v121, v121
	s_nop 0
	v_pk_mul_f32 v[96:97], v[96:97], v[120:121]
	v_rcp_f32_e32 v20, v20
	v_pk_mul_f32 v[116:117], v[96:97], v[116:117]
	v_pk_mul_f32 v[96:97], v[102:103], s[26:27] op_sel_hi:[1,0]
	v_rcp_f32_e32 v21, v21
	v_exp_f32_e32 v96, v96
	v_exp_f32_e32 v97, v97
	v_pk_mul_f32 v[16:17], v[16:17], s[24:25] op_sel_hi:[1,0]
	v_pk_mul_f32 v[20:21], v[40:41], v[20:21] neg_lo:[1,0] neg_hi:[1,0]
	v_pk_mul_f32 v[22:23], v[22:23], s[24:25] op_sel_hi:[1,0]
	v_pk_add_f32 v[96:97], v[96:97], 1.0 op_sel_hi:[1,0] neg_lo:[1,0] neg_hi:[1,0]
	v_exp_f32_e32 v16, v16
	v_max_f32_e32 v96, 0, v96
	v_max_f32_e32 v97, 0, v97
	v_exp_f32_e32 v17, v17
	v_exp_f32_e32 v22, v22
	v_exp_f32_e32 v23, v23
	v_pk_add_f32 v[16:17], v[16:17], 1.0 op_sel_hi:[1,0]
	v_pk_add_f32 v[22:23], v[22:23], 1.0 op_sel_hi:[1,0]
	v_rcp_f32_e32 v16, v16
	v_rcp_f32_e32 v17, v17
	v_rcp_f32_e32 v22, v22
	v_rcp_f32_e32 v23, v23
	v_sqrt_f32_e32 v96, v96
	v_pk_mul_f32 v[22:23], v[42:43], v[22:23]
	v_pk_add_f32 v[18:19], v[18:19], v[46:47]
	v_pk_add_f32 v[12:13], v[12:13], v[64:65]
	s_add_i32 s0, s44, 32
	s_ashr_i32 s1, s0, 31
	v_sqrt_f32_e32 v97, v97
	s_nop 0
	v_pk_mul_f32 v[96:97], v[98:99], v[96:97]
	v_cvt_pk_bf16_f32 v98, v100, v101
	v_cvt_pk_bf16_f32 v100, v106, v107
	v_cvt_pk_bf16_f32 v99, v102, v103
	s_lshl_b64 s[0:1], s[0:1], 14
	v_pk_mul_f32 v[108:109], v[96:97], v[108:109]
	v_cvt_pk_bf16_f32 v96, v104, v105
	v_lshl_add_u64 v[104:105], v[204:205], 0, v[198:199]
	v_lshlrev_b64 v[104:105], 1, v[104:105]
	v_cvt_pk_bf16_f32 v97, v110, v111
	v_lshl_add_u64 v[106:107], s[18:19], 0, v[104:105]
	global_store_dwordx4 v[106:107], v[96:99], off
	v_pk_add_f32 v[106:107], v[86:87], v[70:71]
	v_pk_add_f32 v[86:87], v[84:85], v[68:69]
	v_lshl_add_u64 v[96:97], s[20:21], 0, v[104:105]
	v_exp_f32_e32 v104, v88
	v_exp_f32_e32 v105, v89
	v_cvt_pk_bf16_f32 v103, v108, v109
	v_cvt_pk_bf16_f32 v101, v118, v119
	v_cvt_pk_bf16_f32 v102, v116, v117
	global_store_dwordx4 v[96:97], v[100:103], off
	v_pk_add_f32 v[104:105], v[104:105], 1.0 op_sel_hi:[1,0]
	v_mov_b32_e32 v97, s1
	v_rcp_f32_e32 v104, v104
	v_rcp_f32_e32 v105, v105
	v_or_b32_e32 v96, s0, v190
	v_pk_mul_f32 v[86:87], v[86:87], s[24:25] op_sel_hi:[1,0]
	v_lshlrev_b32_e32 v100, 16, v132
	v_pk_mul_f32 v[84:85], v[60:61], v[104:105] neg_lo:[1,0] neg_hi:[1,0]
	v_exp_f32_e32 v86, v86
	v_pk_mul_f32 v[104:105], v[84:85], s[26:27] op_sel_hi:[1,0]
	v_exp_f32_e32 v87, v87
	v_exp_f32_e32 v104, v104
	v_exp_f32_e32 v105, v105
	v_and_b32_e32 v101, 0xffff0000, v132
	v_pk_add_f32 v[86:87], v[86:87], 1.0 op_sel_hi:[1,0]
	v_lshlrev_b32_e32 v102, 16, v133
	v_pk_add_f32 v[104:105], v[104:105], 1.0 op_sel_hi:[1,0] neg_lo:[1,0] neg_hi:[1,0]
	v_rcp_f32_e32 v86, v86
	v_max_f32_e32 v104, 0, v104
	v_max_f32_e32 v105, 0, v105
	v_rcp_f32_e32 v87, v87
	v_and_b32_e32 v103, 0xffff0000, v133
	v_lshlrev_b32_e32 v98, 16, v134
	v_and_b32_e32 v99, 0xffff0000, v134
	v_lshlrev_b32_e32 v88, 16, v135
	v_and_b32_e32 v89, 0xffff0000, v135
	v_pk_mul_f32 v[18:19], v[18:19], s[24:25] op_sel_hi:[1,0]
	v_exp_f32_e32 v18, v18
	v_exp_f32_e32 v19, v19
	v_sqrt_f32_e32 v104, v104
	v_pk_add_f32 v[18:19], v[18:19], 1.0 op_sel_hi:[1,0]
	v_rcp_f32_e32 v18, v18
	v_rcp_f32_e32 v19, v19
	v_pk_mul_f32 v[12:13], v[12:13], s[24:25] op_sel_hi:[1,0]
	v_pk_add_f32 v[14:15], v[14:15], v[66:67]
	v_sqrt_f32_e32 v105, v105
	s_nop 0
	v_pk_mul_f32 v[86:87], v[86:87], v[104:105]
	v_pk_mul_f32 v[104:105], v[106:107], s[24:25] op_sel_hi:[1,0]
	v_pk_mul_f32 v[86:87], v[86:87], v[100:101]
	v_pk_mul_f32 v[100:101], v[90:91], s[26:27] op_sel_hi:[1,0]
	v_exp_f32_e32 v104, v104
	v_exp_f32_e32 v100, v100
	v_exp_f32_e32 v101, v101
	v_exp_f32_e32 v105, v105
	v_pk_mul_f32 v[14:15], v[14:15], s[24:25] op_sel_hi:[1,0]
	v_pk_add_f32 v[4:5], v[4:5], v[48:49]
	v_pk_add_f32 v[100:101], v[100:101], 1.0 op_sel_hi:[1,0] neg_lo:[1,0] neg_hi:[1,0]
	v_pk_add_f32 v[104:105], v[104:105], 1.0 op_sel_hi:[1,0]
	v_max_f32_e32 v100, 0, v100
	v_max_f32_e32 v101, 0, v101
	v_rcp_f32_e32 v104, v104
	v_rcp_f32_e32 v105, v105
	v_exp_f32_e32 v14, v14
	v_exp_f32_e32 v15, v15
	s_nop 0
	v_pk_add_f32 v[14:15], v[14:15], 1.0 op_sel_hi:[1,0]
	v_rcp_f32_e32 v14, v14
	v_rcp_f32_e32 v15, v15
	s_nop 0
	v_pk_mul_f32 v[14:15], v[62:63], v[14:15]
	v_pk_mul_f32 v[4:5], v[4:5], s[24:25] op_sel_hi:[1,0]
	v_sqrt_f32_e32 v100, v100
	v_exp_f32_e32 v4, v4
	v_exp_f32_e32 v5, v5
	v_pk_add_f32 v[6:7], v[6:7], v[50:51]
	v_pk_add_f32 v[4:5], v[4:5], 1.0 op_sel_hi:[1,0]
	v_pk_add_f32 v[0:1], v[0:1], v[44:45]
	v_sqrt_f32_e32 v101, v101
	s_nop 0
	v_pk_mul_f32 v[100:101], v[104:105], v[100:101]
	v_rcp_f32_e32 v4, v4
	v_pk_mul_f32 v[100:101], v[100:101], v[102:103]
	v_pk_mul_f32 v[102:103], v[80:81], s[26:27] op_sel_hi:[1,0]
	v_rcp_f32_e32 v5, v5
	v_exp_f32_e32 v102, v102
	v_exp_f32_e32 v103, v103
	v_pk_mul_f32 v[0:1], v[0:1], s[24:25] op_sel_hi:[1,0]
	v_pk_mul_f32 v[4:5], v[40:41], v[4:5] neg_lo:[1,0] neg_hi:[1,0]
	v_pk_mul_f32 v[6:7], v[6:7], s[24:25] op_sel_hi:[1,0]
	v_pk_add_f32 v[102:103], v[102:103], 1.0 op_sel_hi:[1,0] neg_lo:[1,0] neg_hi:[1,0]
	v_exp_f32_e32 v0, v0
	v_max_f32_e32 v102, 0, v102
	v_max_f32_e32 v103, 0, v103
	v_exp_f32_e32 v1, v1
	v_exp_f32_e32 v6, v6
	v_exp_f32_e32 v7, v7
	v_pk_add_f32 v[0:1], v[0:1], 1.0 op_sel_hi:[1,0]
	v_pk_add_f32 v[6:7], v[6:7], 1.0 op_sel_hi:[1,0]
	v_rcp_f32_e32 v0, v0
	v_rcp_f32_e32 v1, v1
	v_rcp_f32_e32 v6, v6
	v_rcp_f32_e32 v7, v7
	v_sqrt_f32_e32 v102, v102
	v_pk_mul_f32 v[6:7], v[42:43], v[6:7]
	v_pk_add_f32 v[2:3], v[2:3], v[46:47]
	s_mov_b64 s[8:9], s[38:39]
	v_pk_mul_f32 v[2:3], v[2:3], s[24:25] op_sel_hi:[1,0]
	s_mov_b64 s[44:45], s[34:35]
	v_sqrt_f32_e32 v103, v103
	s_nop 0
	v_pk_mul_f32 v[76:77], v[76:77], v[102:103]
	v_exp_f32_e32 v2, v2
	v_pk_mul_f32 v[98:99], v[76:77], v[98:99]
	v_pk_mul_f32 v[76:77], v[82:83], s[26:27] op_sel_hi:[1,0]
	v_exp_f32_e32 v3, v3
	v_exp_f32_e32 v76, v76
	v_exp_f32_e32 v77, v77
	v_pk_add_f32 v[2:3], v[2:3], 1.0 op_sel_hi:[1,0]
	s_nop 0
	v_rcp_f32_e32 v2, v2
	v_pk_add_f32 v[76:77], v[76:77], 1.0 op_sel_hi:[1,0] neg_lo:[1,0] neg_hi:[1,0]
	v_rcp_f32_e32 v3, v3
	v_max_f32_e32 v76, 0, v76
	v_max_f32_e32 v77, 0, v77
	s_nop 0
	s_nop 0
	s_nop 0
	s_nop 1
	s_nop 1
	v_sqrt_f32_e32 v76, v76
	s_nop 0
	s_nop 1
	s_nop 1
	v_sqrt_f32_e32 v77, v77
	s_nop 0
	v_pk_mul_f32 v[76:77], v[78:79], v[76:77]
	v_cvt_pk_bf16_f32 v78, v80, v81
	v_cvt_pk_bf16_f32 v80, v86, v87
	v_cvt_pk_bf16_f32 v79, v82, v83
	v_cvt_pk_bf16_f32 v82, v98, v99
	v_cvt_pk_bf16_f32 v81, v100, v101
	s_nop 0
	v_pk_mul_f32 v[88:89], v[76:77], v[88:89]
	v_cvt_pk_bf16_f32 v76, v84, v85
	v_lshl_add_u64 v[84:85], v[96:97], 0, v[192:193]
	v_lshlrev_b64 v[84:85], 1, v[84:85]
	v_cvt_pk_bf16_f32 v77, v90, v91
	v_lshl_add_u64 v[86:87], s[18:19], 0, v[84:85]
	v_cvt_pk_bf16_f32 v83, v88, v89
	global_store_dwordx4 v[86:87], v[76:79], off
	s_nop 1
	v_lshl_add_u64 v[76:77], s[20:21], 0, v[84:85]
	global_store_dwordx4 v[76:77], v[80:83], off
	v_pk_add_f32 v[84:85], v[54:55], v[70:71]
	v_pk_add_f32 v[54:55], v[52:53], v[68:69]
	v_exp_f32_e32 v82, v56
	v_exp_f32_e32 v83, v57
	v_pk_mul_f32 v[54:55], v[54:55], s[24:25] op_sel_hi:[1,0]
	v_lshlrev_b32_e32 v78, 16, v112
	v_exp_f32_e32 v54, v54
	v_pk_add_f32 v[82:83], v[82:83], 1.0 op_sel_hi:[1,0]
	v_exp_f32_e32 v55, v55
	v_rcp_f32_e32 v82, v82
	v_rcp_f32_e32 v83, v83
	v_and_b32_e32 v79, 0xffff0000, v112
	v_pk_add_f32 v[54:55], v[54:55], 1.0 op_sel_hi:[1,0]
	v_lshlrev_b32_e32 v80, 16, v113
	v_pk_mul_f32 v[52:53], v[60:61], v[82:83] neg_lo:[1,0] neg_hi:[1,0]
	v_rcp_f32_e32 v54, v54
	v_pk_mul_f32 v[82:83], v[52:53], s[26:27] op_sel_hi:[1,0]
	v_rcp_f32_e32 v55, v55
	v_exp_f32_e32 v82, v82
	v_exp_f32_e32 v83, v83
	v_and_b32_e32 v81, 0xffff0000, v113
	v_lshlrev_b32_e32 v76, 16, v114
	v_and_b32_e32 v77, 0xffff0000, v114
	v_pk_add_f32 v[82:83], v[82:83], 1.0 op_sel_hi:[1,0] neg_lo:[1,0] neg_hi:[1,0]
	v_lshlrev_b32_e32 v56, 16, v115
	v_max_f32_e32 v82, 0, v82
	v_max_f32_e32 v83, 0, v83
	v_and_b32_e32 v57, 0xffff0000, v115
	s_nop 0
	s_nop 0
	s_nop 1
	s_nop 1
	v_sqrt_f32_e32 v82, v82
	s_nop 0
	s_nop 1
	s_nop 1
	v_sqrt_f32_e32 v83, v83
	s_nop 0
	v_pk_mul_f32 v[54:55], v[54:55], v[82:83]
	v_pk_mul_f32 v[82:83], v[84:85], s[24:25] op_sel_hi:[1,0]
	v_pk_mul_f32 v[54:55], v[54:55], v[78:79]
	v_pk_mul_f32 v[78:79], v[58:59], s[26:27] op_sel_hi:[1,0]
	v_exp_f32_e32 v82, v82
	v_exp_f32_e32 v78, v78
	v_exp_f32_e32 v79, v79
	v_exp_f32_e32 v83, v83
	v_pk_add_f32 v[78:79], v[78:79], 1.0 op_sel_hi:[1,0] neg_lo:[1,0] neg_hi:[1,0]
	s_nop 0
	v_max_f32_e32 v78, 0, v78
	v_max_f32_e32 v79, 0, v79
	v_pk_add_f32 v[82:83], v[82:83], 1.0 op_sel_hi:[1,0]
	v_rcp_f32_e32 v82, v82
	v_rcp_f32_e32 v83, v83
	s_nop 0
	s_nop 1
	s_nop 1
	v_sqrt_f32_e32 v78, v78
	s_nop 0
	s_nop 1
	s_nop 1
	v_sqrt_f32_e32 v79, v79
	s_nop 0
	v_pk_mul_f32 v[78:79], v[82:83], v[78:79]
	s_nop 0
	v_pk_mul_f32 v[78:79], v[78:79], v[80:81]
	v_pk_mul_f32 v[80:81], v[36:37], s[26:27] op_sel_hi:[1,0]
	s_nop 0
	v_exp_f32_e32 v80, v80
	v_exp_f32_e32 v81, v81
	s_nop 0
	v_pk_add_f32 v[80:81], v[80:81], 1.0 op_sel_hi:[1,0] neg_lo:[1,0] neg_hi:[1,0]
	s_nop 0
	v_max_f32_e32 v80, 0, v80
	v_max_f32_e32 v81, 0, v81
	s_nop 0
	s_nop 0
	s_nop 0
	s_nop 1
	s_nop 1
	v_sqrt_f32_e32 v80, v80
	s_nop 0
	s_nop 1
	s_nop 1
	v_sqrt_f32_e32 v81, v81
	s_nop 0
	v_pk_mul_f32 v[32:33], v[32:33], v[80:81]
	s_nop 0
	v_pk_mul_f32 v[76:77], v[32:33], v[76:77]
	v_pk_mul_f32 v[32:33], v[38:39], s[26:27] op_sel_hi:[1,0]
	s_nop 0
	v_exp_f32_e32 v32, v32
	v_exp_f32_e32 v33, v33
	s_nop 0
	v_pk_add_f32 v[32:33], v[32:33], 1.0 op_sel_hi:[1,0] neg_lo:[1,0] neg_hi:[1,0]
	s_nop 0
	v_max_f32_e32 v32, 0, v32
	v_max_f32_e32 v33, 0, v33
	s_nop 0
	s_nop 0
	s_nop 0
	s_nop 1
	s_nop 1
	v_sqrt_f32_e32 v32, v32
	s_nop 0
	s_nop 1
	s_nop 1
	v_sqrt_f32_e32 v33, v33
	s_nop 0
	v_pk_mul_f32 v[32:33], v[34:35], v[32:33]
	v_cvt_pk_bf16_f32 v34, v36, v37
	v_cvt_pk_bf16_f32 v36, v54, v55
	v_cvt_pk_bf16_f32 v35, v38, v39
	v_cvt_pk_bf16_f32 v38, v76, v77
	v_cvt_pk_bf16_f32 v37, v78, v79
	s_nop 0
	v_pk_mul_f32 v[56:57], v[32:33], v[56:57]
	v_cvt_pk_bf16_f32 v32, v52, v53
	v_lshl_add_u64 v[52:53], v[96:97], 0, v[194:195]
	v_lshlrev_b64 v[52:53], 1, v[52:53]
	v_cvt_pk_bf16_f32 v33, v58, v59
	v_lshl_add_u64 v[54:55], s[18:19], 0, v[52:53]
	v_cvt_pk_bf16_f32 v39, v56, v57
	global_store_dwordx4 v[54:55], v[32:35], off
	s_nop 1
	v_lshl_add_u64 v[32:33], s[20:21], 0, v[52:53]
	global_store_dwordx4 v[32:33], v[36:39], off
	v_pk_add_f32 v[52:53], v[26:27], v[70:71]
	v_pk_add_f32 v[26:27], v[24:25], v[68:69]
	v_exp_f32_e32 v38, v28
	v_exp_f32_e32 v39, v29
	v_pk_mul_f32 v[26:27], v[26:27], s[24:25] op_sel_hi:[1,0]
	v_lshlrev_b32_e32 v34, 16, v92
	v_exp_f32_e32 v26, v26
	v_pk_add_f32 v[38:39], v[38:39], 1.0 op_sel_hi:[1,0]
	v_exp_f32_e32 v27, v27
	v_rcp_f32_e32 v38, v38
	v_rcp_f32_e32 v39, v39
	v_and_b32_e32 v35, 0xffff0000, v92
	v_pk_add_f32 v[26:27], v[26:27], 1.0 op_sel_hi:[1,0]
	v_lshlrev_b32_e32 v36, 16, v93
	v_pk_mul_f32 v[24:25], v[60:61], v[38:39] neg_lo:[1,0] neg_hi:[1,0]
	v_rcp_f32_e32 v26, v26
	v_pk_mul_f32 v[38:39], v[24:25], s[26:27] op_sel_hi:[1,0]
	v_rcp_f32_e32 v27, v27
	v_exp_f32_e32 v38, v38
	v_exp_f32_e32 v39, v39
	v_and_b32_e32 v37, 0xffff0000, v93
	v_lshlrev_b32_e32 v32, 16, v94
	v_and_b32_e32 v33, 0xffff0000, v94
	v_pk_add_f32 v[38:39], v[38:39], 1.0 op_sel_hi:[1,0] neg_lo:[1,0] neg_hi:[1,0]
	v_lshlrev_b32_e32 v28, 16, v95
	v_max_f32_e32 v38, 0, v38
	v_max_f32_e32 v39, 0, v39
	v_and_b32_e32 v29, 0xffff0000, v95
	s_nop 0
	s_nop 0
	s_nop 1
	s_nop 1
	v_sqrt_f32_e32 v38, v38
	s_nop 0
	s_nop 1
	s_nop 1
	v_sqrt_f32_e32 v39, v39
	s_nop 0
	v_pk_mul_f32 v[26:27], v[26:27], v[38:39]
	v_pk_mul_f32 v[38:39], v[52:53], s[24:25] op_sel_hi:[1,0]
	v_pk_mul_f32 v[26:27], v[26:27], v[34:35]
	v_pk_mul_f32 v[34:35], v[30:31], s[26:27] op_sel_hi:[1,0]
	v_exp_f32_e32 v38, v38
	v_exp_f32_e32 v34, v34
	v_exp_f32_e32 v35, v35
	v_exp_f32_e32 v39, v39
	v_pk_add_f32 v[34:35], v[34:35], 1.0 op_sel_hi:[1,0] neg_lo:[1,0] neg_hi:[1,0]
	s_nop 0
	v_max_f32_e32 v34, 0, v34
	v_max_f32_e32 v35, 0, v35
	v_pk_add_f32 v[38:39], v[38:39], 1.0 op_sel_hi:[1,0]
	v_rcp_f32_e32 v38, v38
	v_rcp_f32_e32 v39, v39
	s_nop 0
	s_nop 1
	s_nop 1
	v_sqrt_f32_e32 v34, v34
	s_nop 0
	s_nop 1
	s_nop 1
	v_sqrt_f32_e32 v35, v35
	s_nop 0
	v_pk_mul_f32 v[34:35], v[38:39], v[34:35]
	s_nop 0
	v_pk_mul_f32 v[34:35], v[34:35], v[36:37]
	v_pk_mul_f32 v[36:37], v[20:21], s[26:27] op_sel_hi:[1,0]
	s_nop 0
	v_exp_f32_e32 v36, v36
	v_exp_f32_e32 v37, v37
	s_nop 0
	v_pk_add_f32 v[36:37], v[36:37], 1.0 op_sel_hi:[1,0] neg_lo:[1,0] neg_hi:[1,0]
	s_nop 0
	v_max_f32_e32 v36, 0, v36
	v_max_f32_e32 v37, 0, v37
	s_nop 0
	s_nop 0
	s_nop 0
	s_nop 1
	s_nop 1
	v_sqrt_f32_e32 v36, v36
	s_nop 0
	s_nop 1
	s_nop 1
	v_sqrt_f32_e32 v37, v37
	s_nop 0
	v_pk_mul_f32 v[16:17], v[16:17], v[36:37]
	s_nop 0
	v_pk_mul_f32 v[32:33], v[16:17], v[32:33]
	v_pk_mul_f32 v[16:17], v[22:23], s[26:27] op_sel_hi:[1,0]
	s_nop 0
	v_exp_f32_e32 v16, v16
	v_exp_f32_e32 v17, v17
	s_nop 0
	v_pk_add_f32 v[16:17], v[16:17], 1.0 op_sel_hi:[1,0] neg_lo:[1,0] neg_hi:[1,0]
	s_nop 0
	v_max_f32_e32 v16, 0, v16
	v_max_f32_e32 v17, 0, v17
	s_nop 0
	s_nop 0
	s_nop 0
	s_nop 1
	s_nop 1
	v_sqrt_f32_e32 v16, v16
	s_nop 0
	s_nop 1
	s_nop 1
	v_sqrt_f32_e32 v17, v17
	s_nop 0
	v_pk_mul_f32 v[16:17], v[18:19], v[16:17]
	v_cvt_pk_bf16_f32 v18, v20, v21
	v_cvt_pk_bf16_f32 v20, v26, v27
	v_cvt_pk_bf16_f32 v19, v22, v23
	v_cvt_pk_bf16_f32 v22, v32, v33
	v_cvt_pk_bf16_f32 v21, v34, v35
	s_nop 0
	v_pk_mul_f32 v[28:29], v[16:17], v[28:29]
	v_cvt_pk_bf16_f32 v16, v24, v25
	v_lshl_add_u64 v[24:25], v[96:97], 0, v[196:197]
	v_lshlrev_b64 v[24:25], 1, v[24:25]
	v_cvt_pk_bf16_f32 v17, v30, v31
	v_lshl_add_u64 v[26:27], s[18:19], 0, v[24:25]
	v_cvt_pk_bf16_f32 v23, v28, v29
	global_store_dwordx4 v[26:27], v[16:19], off
	s_nop 1
	v_lshl_add_u64 v[16:17], s[20:21], 0, v[24:25]
	global_store_dwordx4 v[16:17], v[20:23], off
	v_pk_add_f32 v[24:25], v[10:11], v[70:71]
	v_pk_add_f32 v[10:11], v[8:9], v[68:69]
	v_exp_f32_e32 v22, v12
	v_exp_f32_e32 v23, v13
	v_pk_mul_f32 v[10:11], v[10:11], s[24:25] op_sel_hi:[1,0]
	v_lshlrev_b32_e32 v18, 16, v72
	v_exp_f32_e32 v10, v10
	v_pk_add_f32 v[22:23], v[22:23], 1.0 op_sel_hi:[1,0]
	v_exp_f32_e32 v11, v11
	v_rcp_f32_e32 v22, v22
	v_rcp_f32_e32 v23, v23
	v_and_b32_e32 v19, 0xffff0000, v72
	v_pk_add_f32 v[10:11], v[10:11], 1.0 op_sel_hi:[1,0]
	v_lshlrev_b32_e32 v20, 16, v73
	v_pk_mul_f32 v[8:9], v[60:61], v[22:23] neg_lo:[1,0] neg_hi:[1,0]
	v_rcp_f32_e32 v10, v10
	v_pk_mul_f32 v[22:23], v[8:9], s[26:27] op_sel_hi:[1,0]
	v_rcp_f32_e32 v11, v11
	v_exp_f32_e32 v22, v22
	v_exp_f32_e32 v23, v23
	v_and_b32_e32 v21, 0xffff0000, v73
	v_lshlrev_b32_e32 v16, 16, v74
	v_and_b32_e32 v17, 0xffff0000, v74
	v_pk_add_f32 v[22:23], v[22:23], 1.0 op_sel_hi:[1,0] neg_lo:[1,0] neg_hi:[1,0]
	v_lshlrev_b32_e32 v12, 16, v75
	v_max_f32_e32 v22, 0, v22
	v_max_f32_e32 v23, 0, v23
	v_and_b32_e32 v13, 0xffff0000, v75
	s_nop 0
	s_nop 0
	s_nop 1
	s_nop 1
	v_sqrt_f32_e32 v22, v22
	s_nop 0
	s_nop 1
	s_nop 1
	v_sqrt_f32_e32 v23, v23
	s_nop 0
	v_pk_mul_f32 v[10:11], v[10:11], v[22:23]
	v_pk_mul_f32 v[22:23], v[24:25], s[24:25] op_sel_hi:[1,0]
	v_pk_mul_f32 v[10:11], v[10:11], v[18:19]
	v_pk_mul_f32 v[18:19], v[14:15], s[26:27] op_sel_hi:[1,0]
	v_exp_f32_e32 v22, v22
	v_exp_f32_e32 v18, v18
	v_exp_f32_e32 v19, v19
	v_exp_f32_e32 v23, v23
	v_pk_add_f32 v[18:19], v[18:19], 1.0 op_sel_hi:[1,0] neg_lo:[1,0] neg_hi:[1,0]
	s_nop 0
	v_max_f32_e32 v18, 0, v18
	v_max_f32_e32 v19, 0, v19
	v_pk_add_f32 v[22:23], v[22:23], 1.0 op_sel_hi:[1,0]
	v_rcp_f32_e32 v22, v22
	v_rcp_f32_e32 v23, v23
	s_nop 0
	s_nop 1
	s_nop 1
	v_sqrt_f32_e32 v18, v18
	s_nop 0
	s_nop 1
	s_nop 1
	v_sqrt_f32_e32 v19, v19
	s_nop 0
	v_pk_mul_f32 v[18:19], v[22:23], v[18:19]
	s_nop 0
	v_pk_mul_f32 v[18:19], v[18:19], v[20:21]
	v_pk_mul_f32 v[20:21], v[4:5], s[26:27] op_sel_hi:[1,0]
	s_nop 0
	v_exp_f32_e32 v20, v20
	v_exp_f32_e32 v21, v21
	s_nop 0
	v_pk_add_f32 v[20:21], v[20:21], 1.0 op_sel_hi:[1,0] neg_lo:[1,0] neg_hi:[1,0]
	s_nop 0
	v_max_f32_e32 v20, 0, v20
	v_max_f32_e32 v21, 0, v21
	s_nop 0
	s_nop 0
	s_nop 0
	s_nop 1
	s_nop 1
	v_sqrt_f32_e32 v20, v20
	s_nop 0
	s_nop 1
	s_nop 1
	v_sqrt_f32_e32 v21, v21
	s_nop 0
	v_pk_mul_f32 v[0:1], v[0:1], v[20:21]
	s_nop 0
	v_pk_mul_f32 v[16:17], v[0:1], v[16:17]
	v_pk_mul_f32 v[0:1], v[6:7], s[26:27] op_sel_hi:[1,0]
	s_nop 0
	v_exp_f32_e32 v0, v0
	v_exp_f32_e32 v1, v1
	s_nop 0
	v_pk_add_f32 v[0:1], v[0:1], 1.0 op_sel_hi:[1,0] neg_lo:[1,0] neg_hi:[1,0]
	s_nop 0
	v_max_f32_e32 v0, 0, v0
	v_max_f32_e32 v1, 0, v1
	s_nop 0
	s_nop 0
	s_nop 0
	s_nop 1
	s_nop 1
	v_sqrt_f32_e32 v0, v0
	s_nop 0
	s_nop 1
	s_mov_b32 s1, s28
	s_mov_b32 s0, s30
	v_sqrt_f32_e32 v1, v1
	s_nop 0
	v_pk_mul_f32 v[0:1], v[2:3], v[0:1]
	v_cvt_pk_bf16_f32 v2, v4, v5
	v_cvt_pk_bf16_f32 v4, v10, v11
	v_cvt_pk_bf16_f32 v3, v6, v7
	s_and_b64 vcc, exec, s[6:7]
	v_pk_mul_f32 v[12:13], v[0:1], v[12:13]
	v_cvt_pk_bf16_f32 v0, v8, v9
	v_lshl_add_u64 v[8:9], v[96:97], 0, v[198:199]
	v_lshlrev_b64 v[8:9], 1, v[8:9]
	v_cvt_pk_bf16_f32 v1, v14, v15
	v_lshl_add_u64 v[10:11], s[18:19], 0, v[8:9]
	global_store_dwordx4 v[10:11], v[0:3], off
	v_cvt_pk_bf16_f32 v5, v18, v19
	v_cvt_pk_bf16_f32 v6, v16, v17
	v_cvt_pk_bf16_f32 v7, v12, v13
	s_nop 1
	v_lshl_add_u64 v[0:1], s[20:21], 0, v[8:9]
	global_store_dwordx4 v[0:1], v[4:7], off
	s_cbranch_vccz .LBB0_459
	s_waitcnt vmcnt(0)
	s_cmpk_gt_u32 s10, 0xff
	s_cbranch_scc1 .LBB0_470
	s_barrier
